# EpiRes bf16 h stores widened: v_permlane16_swap pairs then one dwordx4 per row block half (FFN-down and out-proj), on top of gate+convert rewrites
# speedup vs baseline: 1.0126x; 1.0126x over previous
; #define LAS __attribute__((address_space(3)))
; DI unsigned cvt_pk(float lo, float hi) { unsigned r; asm("v_cvt_pk_bf16_f32 %0, %1, %2" : "=v"(r) : "v"(lo), "v"(hi)); return r; }
; #define EPI_FENCE asm volatile("" ::: "memory")
;   DI void operator()(LAS unsigned char* lds, f32x4 (&acc)[2][2][4][2], int pm, int pn, int wr, int wc, int fr, int fq) const {
;     const size_t base0 = (size_t)(pm * BM + wr * 64 + fr) * DM + pn * BM + wc * 32 + fq * 4;
;     LAS float* red = (LAS float*)(lds + 131072);
; #pragma unroll
;     for (int ai = 0; ai < 2; ++ai) {
;       f32x4 rv[4][2][2];
; #pragma unroll
;       for (int m = 0; m < 4; ++m)
; #pragma unroll
;         for (int bj = 0; bj < 2; ++bj)
; #pragma unroll
;           for (int n = 0; n < 2; ++n) rv[m][bj][n] = *(const f32x4*)(resid + base0 + (size_t)(ai * HALF + m * 16) * DM + bj * HALF + n * 16);
;       EPI_FENCE;
; #pragma unroll
;       for (int m = 0; m < 4; ++m) {
;         const size_t off0 = base0 + (size_t)(ai * HALF + m * 16) * DM;
;         float* op = hout + off0; bf16_t* bp = hb + off0;
;         float q = 0.f;
; #pragma unroll
;         for (int bj = 0; bj < 2; ++bj)
; #pragma unroll
;           for (int n = 0; n < 2; ++n) {
;             const f32x4 o = rv[m][bj][n] + acc[ai][bj][m][n];
;             *(f32x4*)(op + bj * HALF + n * 16) = o;
;             q += o[0] * o[0] + o[1] * o[1] + o[2] * o[2] + o[3] * o[3];
;             u32x2 w; w.x = cvt_pk(o[0], o[1]); w.y = cvt_pk(o[2], o[3]);
;             *(u32x2*)(bp + bj * HALF + n * 16) = w;
;           }
;         q += __shfl_xor(q, 16); q += __shfl_xor(q, 32);
;         if (fq == 0) red[(ai * HALF + wr * 64 + m * 16 + fr) * 4 + wc] = q;
;       }
.LBB0_107:
	s_or_b64 exec, exec, s[42:43]
	v_bfe_u32 v228, v220, 4, 1
	v_mul_u32_u24_e32 v228, 24, v228
	v_mov_b32_e32 v229, 0
	s_lshl_b32 s20, s20, 8
	v_add_u32_e32 v82, s20, v218
	v_or_b32_e32 v82, v82, v213
	v_ashrrev_i32_e32 v83, 31, v82
	v_lshlrev_b64 v[82:83], 10, v[82:83]
	v_lshlrev_b32_e32 v84, 5, v210
	v_lshl_add_u64 v[180:181], v[82:83], 0, s[18:19]
	v_lshlrev_b32_e32 v82, 2, v212
	v_or3_b32 v180, v180, v84, v82
	v_lshl_add_u64 v[178:179], v[180:181], 2, s[4:5]
	global_load_dwordx4 v[184:187], v[178:179], off
	global_load_dwordx4 v[188:191], v[178:179], off offset:64
	global_load_dwordx4 v[192:195], v[178:179], off offset:512
	global_load_dwordx4 v[196:199], v[178:179], off offset:576
	v_add_co_u32_e32 v82, vcc, s54, v178
	s_mov_b32 s18, 0x20000
	s_nop 0
	v_addc_co_u32_e32 v83, vcc, 0, v179, vcc
	v_add_co_u32_e32 v84, vcc, s18, v178
	v_xor_b32_e32 v200, 32, v224
	s_nop 0
	v_addc_co_u32_e32 v85, vcc, 0, v179, vcc
	v_add_co_u32_e32 v182, vcc, s61, v178
	s_add_i32 s18, 0, 0x20000
	s_nop 0
	v_addc_co_u32_e32 v183, vcc, 0, v179, vcc
	global_load_dwordx4 v[174:177], v[82:83], off
	global_load_dwordx4 v[170:173], v[82:83], off offset:64
	global_load_dwordx4 v[166:169], v[82:83], off offset:512
	global_load_dwordx4 v[154:157], v[82:83], off offset:576
	global_load_dwordx4 v[142:145], v[84:85], off
	global_load_dwordx4 v[134:137], v[84:85], off offset:64
	global_load_dwordx4 v[122:125], v[84:85], off offset:512
	global_load_dwordx4 v[114:117], v[84:85], off offset:576
	global_load_dwordx4 v[110:113], v[182:183], off
	global_load_dwordx4 v[102:105], v[182:183], off offset:64
	global_load_dwordx4 v[94:97], v[182:183], off offset:512
	s_nop 0
	global_load_dwordx4 v[82:85], v[182:183], off offset:576
	v_and_b32_e32 v183, 64, v224
	v_xor_b32_e32 v182, 16, v224
	v_add_u32_e32 v183, 64, v183
	v_cmp_lt_i32_e32 vcc, v182, v183
	v_lshl_add_u32 v201, v210, 2, s18
	v_cmp_eq_u32_e64 s[42:43], 0, v212
	v_cndmask_b32_e32 v182, v224, v182, vcc
	v_lshlrev_b32_e32 v182, 2, v182
	v_cmp_lt_i32_e32 vcc, v200, v183
	v_lshl_add_u64 v[180:181], v[180:181], 1, s[58:59]
	v_lshl_add_u32 v0, v0, 4, v201
	v_cndmask_b32_e32 v183, v224, v200, vcc
	s_waitcnt vmcnt(0)
	v_pk_add_f32 v[148:149], v[148:149], v[186:187]
	v_pk_add_f32 v[146:147], v[146:147], v[184:185]
	v_pk_add_f32 v[150:151], v[150:151], v[188:189]
	v_pk_add_f32 v[152:153], v[152:153], v[190:191]
	v_pk_add_f32 v[158:159], v[158:159], v[192:193]
	global_store_dwordx4 v[178:179], v[146:149], off
	v_mul_f32_e32 v190, v147, v147
	v_cvt_pk_bf16_f32 v184, v146, v147
	v_pk_add_f32 v[162:163], v[162:163], v[196:197]
	v_mul_f32_e32 v147, v151, v151
	v_mul_f32_e32 v191, v159, v159
	v_fmac_f32_e32 v190, v146, v146
	v_fmac_f32_e32 v147, v150, v150
	v_pk_add_f32 v[160:161], v[160:161], v[194:195]
	v_mul_f32_e32 v192, v163, v163
	v_fmac_f32_e32 v191, v158, v158
	v_fmac_f32_e32 v190, v148, v148
	v_fmac_f32_e32 v147, v152, v152
	v_pk_add_f32 v[164:165], v[164:165], v[198:199]
	v_fmac_f32_e32 v192, v162, v162
	v_fmac_f32_e32 v191, v160, v160
	v_fmac_f32_e32 v190, v149, v149
	v_fmac_f32_e32 v147, v153, v153
	v_fmac_f32_e32 v192, v164, v164
	v_fmac_f32_e32 v191, v161, v161
	v_add_f32_e32 v146, v190, v147
	v_fmac_f32_e32 v192, v165, v165
	v_add_f32_e32 v146, v146, v191
	v_add_f32_e32 v146, v146, v192
	ds_bpermute_b32 v147, v182, v146
	v_cvt_pk_bf16_f32 v185, v148, v149
	v_cvt_pk_bf16_f32 v186, v150, v151
	v_cvt_pk_bf16_f32 v187, v152, v153
	v_cvt_pk_bf16_f32 v188, v158, v159
	s_waitcnt lgkmcnt(0)
	v_add_f32_e32 v147, v146, v147
	v_lshlrev_b32_e32 v146, 2, v183
	ds_bpermute_b32 v148, v146, v147
	v_cvt_pk_bf16_f32 v189, v160, v161
	v_mov_b32_e32 v232, v184
	v_mov_b32_e32 v233, v185
	global_store_dwordx4 v[178:179], v[150:153], off offset:64
	v_mov_b32_e32 v234, v186
	v_mov_b32_e32 v235, v187
	global_store_dwordx4 v[178:179], v[158:161], off offset:512
	v_mov_b32_e32 v236, v188
	v_mov_b32_e32 v237, v189
	global_store_dwordx4 v[178:179], v[162:165], off offset:576
	v_cvt_pk_bf16_f32 v150, v162, v163
	v_cvt_pk_bf16_f32 v151, v164, v165
	v_mov_b32_e32 v238, v150
	v_mov_b32_e32 v239, v151
	v_lshl_add_u64 v[230:231], v[180:181], 0, v[228:229]
	s_waitcnt lgkmcnt(0)
	s_nop 1
	v_permlane16_swap_b32_e32 v232, v234
	v_permlane16_swap_b32_e32 v233, v235
	v_permlane16_swap_b32_e32 v236, v238
	v_permlane16_swap_b32_e32 v237, v239
	global_store_dwordx4 v[230:231], v[232:235], off
	global_store_dwordx4 v[230:231], v[236:239], off offset:256
	s_and_saveexec_b64 s[18:19], s[42:43]
	s_cbranch_execz .LBB0_109
	s_waitcnt lgkmcnt(0)
	v_add_f32_e32 v147, v147, v148
	ds_write_b32 v0, v147
; DI unsigned cvt_pk(float lo, float hi) { unsigned r; asm("v_cvt_pk_bf16_f32 %0, %1, %2" : "=v"(r) : "v"(lo), "v"(hi)); return r; }
;   DI void operator()(LAS unsigned char* lds, f32x4 (&acc)[2][2][4][2], int pm, int pn, int wr, int wc, int fr, int fq) const {
;     ...
;       for (int m = 0; m < 4; ++m) {
;         const size_t off0 = base0 + (size_t)(ai * HALF + m * 16) * DM;
;         float* op = hout + off0; bf16_t* bp = hb + off0;
;         float q = 0.f;
; #pragma unroll
;         for (int bj = 0; bj < 2; ++bj)
; #pragma unroll
;           for (int n = 0; n < 2; ++n) {
;             const f32x4 o = rv[m][bj][n] + acc[ai][bj][m][n];
;             *(f32x4*)(op + bj * HALF + n * 16) = o;
;             q += o[0] * o[0] + o[1] * o[1] + o[2] * o[2] + o[3] * o[3];
;             u32x2 w; w.x = cvt_pk(o[0], o[1]); w.y = cvt_pk(o[2], o[3]);
;             *(u32x2*)(bp + bj * HALF + n * 16) = w;
;           }
;         q += __shfl_xor(q, 16); q += __shfl_xor(q, 32);
;         if (fq == 0) red[(ai * HALF + wr * 64 + m * 16 + fr) * 4 + wc] = q;
;       }
.LBB0_109:
	s_or_b64 exec, exec, s[18:19]
	v_pk_add_f32 v[138:139], v[138:139], v[174:175]
	s_mov_b64 s[18:19], 0x10000
	v_mul_f32_e32 v147, v139, v139
	s_waitcnt lgkmcnt(0)
	v_lshl_add_u64 v[148:149], v[178:179], 0, s[18:19]
	v_pk_add_f32 v[140:141], v[140:141], v[176:177]
	v_fmac_f32_e32 v147, v138, v138
	global_store_dwordx4 v[148:149], v[138:141], off
	v_fmac_f32_e32 v147, v140, v140
	v_fmac_f32_e32 v147, v141, v141
	v_cvt_pk_bf16_f32 v138, v138, v139
	v_cvt_pk_bf16_f32 v139, v140, v141
	v_add_co_u32_e32 v140, vcc, s57, v180
	v_pk_add_f32 v[126:127], v[126:127], v[170:171]
	s_nop 0
	v_addc_co_u32_e32 v141, vcc, 0, v181, vcc
	s_mov_b64 s[18:19], 0x8000
	v_mov_b32_e32 v240, v138
	v_mov_b32_e32 v241, v139
	v_pk_add_f32 v[128:129], v[128:129], v[172:173]
	v_mul_f32_e32 v138, v127, v127
	v_lshl_add_u64 v[150:151], v[180:181], 0, s[18:19]
	global_store_dwordx4 v[148:149], v[126:129], off offset:64
	v_fmac_f32_e32 v138, v126, v126
	v_fmac_f32_e32 v138, v128, v128
	v_cvt_pk_bf16_f32 v126, v126, v127
	v_cvt_pk_bf16_f32 v127, v128, v129
	v_mov_b32_e32 v242, v126
	v_mov_b32_e32 v243, v127
	v_pk_add_f32 v[126:127], v[130:131], v[166:167]
	v_fmac_f32_e32 v138, v129, v129
	v_mul_f32_e32 v130, v127, v127
	v_pk_add_f32 v[128:129], v[132:133], v[168:169]
	v_fmac_f32_e32 v130, v126, v126
	v_fmac_f32_e32 v130, v128, v128
	v_add_f32_e32 v138, v147, v138
	v_fmac_f32_e32 v130, v129, v129
	v_add_f32_e32 v138, v138, v130
	v_pk_add_f32 v[130:131], v[118:119], v[154:155]
	v_pk_add_f32 v[132:133], v[120:121], v[156:157]
	v_mul_f32_e32 v118, v131, v131
	v_fmac_f32_e32 v118, v130, v130
	v_fmac_f32_e32 v118, v132, v132
	v_fmac_f32_e32 v118, v133, v133
	v_add_f32_e32 v120, v138, v118
	ds_bpermute_b32 v121, v182, v120
	v_cvt_pk_bf16_f32 v118, v126, v127
	global_store_dwordx4 v[148:149], v[126:129], off offset:512
	v_cvt_pk_bf16_f32 v119, v128, v129
	v_mov_b32_e32 v244, v118
	v_mov_b32_e32 v245, v119
	s_waitcnt lgkmcnt(0)
	v_add_f32_e32 v118, v120, v121
	ds_bpermute_b32 v119, v146, v118
	global_store_dwordx4 v[148:149], v[130:133], off offset:576
	v_cvt_pk_bf16_f32 v120, v130, v131
	v_cvt_pk_bf16_f32 v121, v132, v133
	v_mov_b32_e32 v246, v120
	v_mov_b32_e32 v247, v121
	v_lshl_add_u64 v[230:231], v[150:151], 0, v[228:229]
	s_waitcnt lgkmcnt(0)
	s_nop 1
	v_permlane16_swap_b32_e32 v240, v242
	v_permlane16_swap_b32_e32 v241, v243
	v_permlane16_swap_b32_e32 v244, v246
	v_permlane16_swap_b32_e32 v245, v247
	global_store_dwordx4 v[230:231], v[240:243], off
	global_store_dwordx4 v[230:231], v[244:247], off offset:256
	s_and_saveexec_b64 s[18:19], s[42:43]
	s_cbranch_execz .LBB0_111
	s_waitcnt lgkmcnt(0)
	v_add_f32_e32 v118, v118, v119
	ds_write_b32 v0, v118 offset:256
.LBB0_111:
	s_or_b64 exec, exec, s[18:19]
	v_pk_add_f32 v[106:107], v[106:107], v[142:143]
	s_mov_b64 s[18:19], 0x20000
	v_mul_f32_e32 v126, v107, v107
	s_waitcnt lgkmcnt(0)
	v_lshl_add_u64 v[118:119], v[178:179], 0, s[18:19]
	v_pk_add_f32 v[108:109], v[108:109], v[144:145]
	v_fmac_f32_e32 v126, v106, v106
	global_store_dwordx4 v[118:119], v[106:109], off
	v_fmac_f32_e32 v126, v108, v108
	v_fmac_f32_e32 v126, v109, v109
	v_cvt_pk_bf16_f32 v106, v106, v107
	v_cvt_pk_bf16_f32 v107, v108, v109
	v_add_co_u32_e32 v108, vcc, s54, v180
	v_pk_add_f32 v[90:91], v[90:91], v[134:135]
	s_nop 0
	v_addc_co_u32_e32 v109, vcc, 0, v181, vcc
	s_mov_b64 s[18:19], 0x10000
	v_mov_b32_e32 v232, v106
	v_mov_b32_e32 v233, v107
	v_pk_add_f32 v[92:93], v[92:93], v[136:137]
	v_mul_f32_e32 v106, v91, v91
	v_lshl_add_u64 v[120:121], v[180:181], 0, s[18:19]
	global_store_dwordx4 v[118:119], v[90:93], off offset:64
	v_fmac_f32_e32 v106, v90, v90
	v_fmac_f32_e32 v106, v92, v92
	v_cvt_pk_bf16_f32 v90, v90, v91
	v_cvt_pk_bf16_f32 v91, v92, v93
	v_mov_b32_e32 v234, v90
	v_mov_b32_e32 v235, v91
	v_pk_add_f32 v[90:91], v[98:99], v[122:123]
	v_fmac_f32_e32 v106, v93, v93
	v_mul_f32_e32 v98, v91, v91
	v_pk_add_f32 v[92:93], v[100:101], v[124:125]
	v_fmac_f32_e32 v98, v90, v90
	v_fmac_f32_e32 v98, v92, v92
	v_add_f32_e32 v106, v126, v106
	v_fmac_f32_e32 v98, v93, v93
	v_add_f32_e32 v106, v106, v98
	v_pk_add_f32 v[98:99], v[86:87], v[114:115]
	v_pk_add_f32 v[100:101], v[88:89], v[116:117]
	v_mul_f32_e32 v86, v99, v99
	v_fmac_f32_e32 v86, v98, v98
	v_fmac_f32_e32 v86, v100, v100
	v_fmac_f32_e32 v86, v101, v101
	v_add_f32_e32 v88, v106, v86
	ds_bpermute_b32 v89, v182, v88
	v_cvt_pk_bf16_f32 v86, v90, v91
	global_store_dwordx4 v[118:119], v[90:93], off offset:512
	v_cvt_pk_bf16_f32 v87, v92, v93
	v_mov_b32_e32 v236, v86
	v_mov_b32_e32 v237, v87
	s_waitcnt lgkmcnt(0)
	v_add_f32_e32 v86, v88, v89
	ds_bpermute_b32 v87, v146, v86
	global_store_dwordx4 v[118:119], v[98:101], off offset:576
	v_cvt_pk_bf16_f32 v88, v98, v99
	v_cvt_pk_bf16_f32 v89, v100, v101
	v_mov_b32_e32 v238, v88
	v_mov_b32_e32 v239, v89
	v_lshl_add_u64 v[230:231], v[120:121], 0, v[228:229]
	s_waitcnt lgkmcnt(0)
	s_nop 1
	v_permlane16_swap_b32_e32 v232, v234
	v_permlane16_swap_b32_e32 v233, v235
	v_permlane16_swap_b32_e32 v236, v238
	v_permlane16_swap_b32_e32 v237, v239
	global_store_dwordx4 v[230:231], v[232:235], off
	global_store_dwordx4 v[230:231], v[236:239], off offset:256
	s_and_saveexec_b64 s[18:19], s[42:43]
	s_cbranch_execz .LBB0_113
	s_waitcnt lgkmcnt(0)
	v_add_f32_e32 v86, v86, v87
	ds_write_b32 v0, v86 offset:512
; DI unsigned cvt_pk(float lo, float hi) { unsigned r; asm("v_cvt_pk_bf16_f32 %0, %1, %2" : "=v"(r) : "v"(lo), "v"(hi)); return r; }
; #define EPI_FENCE asm volatile("" ::: "memory")
;   DI void operator()(LAS unsigned char* lds, f32x4 (&acc)[2][2][4][2], int pm, int pn, int wr, int wc, int fr, int fq) const {
;     ...
; #pragma unroll
;     for (int ai = 0; ai < 2; ++ai) {
;       f32x4 rv[4][2][2];
; #pragma unroll
;       for (int m = 0; m < 4; ++m)
; #pragma unroll
;         for (int bj = 0; bj < 2; ++bj)
; #pragma unroll
;           for (int n = 0; n < 2; ++n) rv[m][bj][n] = *(const f32x4*)(resid + base0 + (size_t)(ai * HALF + m * 16) * DM + bj * HALF + n * 16);
;       EPI_FENCE;
; #pragma unroll
;       for (int m = 0; m < 4; ++m) {
;         const size_t off0 = base0 + (size_t)(ai * HALF + m * 16) * DM;
;         float* op = hout + off0; bf16_t* bp = hb + off0;
;         float q = 0.f;
; #pragma unroll
;         for (int bj = 0; bj < 2; ++bj)
; #pragma unroll
;           for (int n = 0; n < 2; ++n) {
;             const f32x4 o = rv[m][bj][n] + acc[ai][bj][m][n];
;             *(f32x4*)(op + bj * HALF + n * 16) = o;
;             q += o[0] * o[0] + o[1] * o[1] + o[2] * o[2] + o[3] * o[3];
;             u32x2 w; w.x = cvt_pk(o[0], o[1]); w.y = cvt_pk(o[2], o[3]);
;             *(u32x2*)(bp + bj * HALF + n * 16) = w;
;           }
;         q += __shfl_xor(q, 16); q += __shfl_xor(q, 32);
;         if (fq == 0) red[(ai * HALF + wr * 64 + m * 16 + fr) * 4 + wc] = q;
;       }
.LBB0_113:
	s_or_b64 exec, exec, s[18:19]
	v_pk_add_f32 v[78:79], v[78:79], v[110:111]
	s_mov_b64 s[18:19], 0x30000
	v_mul_f32_e32 v90, v79, v79
	s_waitcnt lgkmcnt(0)
	v_lshl_add_u64 v[86:87], v[178:179], 0, s[18:19]
	v_pk_add_f32 v[80:81], v[80:81], v[112:113]
	v_fmac_f32_e32 v90, v78, v78
	global_store_dwordx4 v[86:87], v[78:81], off
	v_fmac_f32_e32 v90, v80, v80
	v_fmac_f32_e32 v90, v81, v81
	v_cvt_pk_bf16_f32 v78, v78, v79
	v_cvt_pk_bf16_f32 v79, v80, v81
	v_add_co_u32_e32 v80, vcc, s56, v180
	v_pk_add_f32 v[70:71], v[70:71], v[102:103]
	s_nop 0
	v_addc_co_u32_e32 v81, vcc, 0, v181, vcc
	s_mov_b64 s[18:19], 0x18000
	v_mov_b32_e32 v240, v78
	v_mov_b32_e32 v241, v79
	v_pk_add_f32 v[72:73], v[72:73], v[104:105]
	v_mul_f32_e32 v78, v71, v71
	v_lshl_add_u64 v[88:89], v[180:181], 0, s[18:19]
	global_store_dwordx4 v[86:87], v[70:73], off offset:64
	v_fmac_f32_e32 v78, v70, v70
	v_fmac_f32_e32 v78, v72, v72
	v_cvt_pk_bf16_f32 v70, v70, v71
	v_cvt_pk_bf16_f32 v71, v72, v73
	v_mov_b32_e32 v242, v70
	v_mov_b32_e32 v243, v71
	v_pk_add_f32 v[70:71], v[74:75], v[94:95]
	v_fmac_f32_e32 v78, v73, v73
	v_mul_f32_e32 v74, v71, v71
	v_pk_add_f32 v[72:73], v[76:77], v[96:97]
	v_fmac_f32_e32 v74, v70, v70
	v_fmac_f32_e32 v74, v72, v72
	v_add_f32_e32 v78, v90, v78
	v_fmac_f32_e32 v74, v73, v73
	v_add_f32_e32 v78, v78, v74
	v_pk_add_f32 v[74:75], v[66:67], v[82:83]
	v_pk_add_f32 v[76:77], v[68:69], v[84:85]
	v_mul_f32_e32 v66, v75, v75
	v_fmac_f32_e32 v66, v74, v74
	v_fmac_f32_e32 v66, v76, v76
	v_fmac_f32_e32 v66, v77, v77
	v_add_f32_e32 v68, v78, v66
	ds_bpermute_b32 v69, v182, v68
	v_cvt_pk_bf16_f32 v66, v70, v71
	global_store_dwordx4 v[86:87], v[70:73], off offset:512
	v_cvt_pk_bf16_f32 v67, v72, v73
	v_mov_b32_e32 v244, v66
	v_mov_b32_e32 v245, v67
	s_waitcnt lgkmcnt(0)
	v_add_f32_e32 v66, v68, v69
	ds_bpermute_b32 v67, v146, v66
	global_store_dwordx4 v[86:87], v[74:77], off offset:576
	v_cvt_pk_bf16_f32 v68, v74, v75
	v_cvt_pk_bf16_f32 v69, v76, v77
	v_mov_b32_e32 v246, v68
	v_mov_b32_e32 v247, v69
	v_lshl_add_u64 v[230:231], v[88:89], 0, v[228:229]
	s_waitcnt lgkmcnt(0)
	s_nop 1
	v_permlane16_swap_b32_e32 v240, v242
	v_permlane16_swap_b32_e32 v241, v243
	v_permlane16_swap_b32_e32 v244, v246
	v_permlane16_swap_b32_e32 v245, v247
	global_store_dwordx4 v[230:231], v[240:243], off
	global_store_dwordx4 v[230:231], v[244:247], off offset:256
	s_and_saveexec_b64 s[18:19], s[42:43]
	s_cbranch_execz .LBB0_115
	s_waitcnt lgkmcnt(0)
	v_add_f32_e32 v66, v66, v67
	ds_write_b32 v0, v66 offset:768
.LBB0_115:
	s_or_b64 exec, exec, s[18:19]
	v_add_co_u32_e32 v134, vcc, 0x80000, v178
	s_mov_b64 s[18:19], 0x80000
	s_nop 0
	v_addc_co_u32_e32 v135, vcc, 0, v179, vcc
	global_load_dwordx4 v[126:129], v[134:135], off
	global_load_dwordx4 v[130:133], v[134:135], off offset:64
	global_load_dwordx4 v[118:121], v[134:135], off offset:512
	global_load_dwordx4 v[114:117], v[134:135], off offset:576
	v_add_co_u32_e32 v66, vcc, 0x90000, v178
	v_lshl_add_u64 v[122:123], v[178:179], 0, s[18:19]
	s_waitcnt lgkmcnt(0)
	v_addc_co_u32_e32 v67, vcc, 0, v179, vcc
	global_load_dwordx4 v[110:113], v[66:67], off
	global_load_dwordx4 v[106:109], v[66:67], off offset:64
	global_load_dwordx4 v[102:105], v[66:67], off offset:512
	global_load_dwordx4 v[98:101], v[66:67], off offset:576
	v_add_co_u32_e32 v66, vcc, 0xa0000, v178
	s_mov_b64 s[18:19], 0x40000
	s_nop 0
	v_addc_co_u32_e32 v67, vcc, 0, v179, vcc
	global_load_dwordx4 v[94:97], v[66:67], off
	global_load_dwordx4 v[90:93], v[66:67], off offset:64
	global_load_dwordx4 v[86:89], v[66:67], off offset:512
	global_load_dwordx4 v[78:81], v[66:67], off offset:576
	v_add_co_u32_e32 v66, vcc, 0xb0000, v178
	v_lshl_add_u64 v[124:125], v[180:181], 0, s[18:19]
	s_nop 0
	v_addc_co_u32_e32 v67, vcc, 0, v179, vcc
	global_load_dwordx4 v[82:85], v[66:67], off
	global_load_dwordx4 v[74:77], v[66:67], off offset:64
	global_load_dwordx4 v[70:73], v[66:67], off offset:512
	s_nop 0
	global_load_dwordx4 v[66:69], v[66:67], off offset:576
	s_waitcnt vmcnt(15)
	v_pk_add_f32 v[62:63], v[62:63], v[126:127]
	s_nop 0
	v_mul_f32_e32 v126, v63, v63
	v_pk_add_f32 v[64:65], v[64:65], v[128:129]
	v_fmac_f32_e32 v126, v62, v62
	global_store_dwordx4 v[134:135], v[62:65], off
	v_fmac_f32_e32 v126, v64, v64
	v_fmac_f32_e32 v126, v65, v65
	v_cvt_pk_bf16_f32 v62, v62, v63
	v_cvt_pk_bf16_f32 v63, v64, v65
	v_add_co_u32_e32 v64, vcc, s62, v180
	s_waitcnt vmcnt(15)
	v_pk_add_f32 v[58:59], v[58:59], v[130:131]
	v_addc_co_u32_e32 v65, vcc, 0, v181, vcc
	v_mov_b32_e32 v232, v62
	v_mov_b32_e32 v233, v63
	v_pk_add_f32 v[60:61], v[60:61], v[132:133]
	v_mul_f32_e32 v62, v59, v59
	global_store_dwordx4 v[122:123], v[58:61], off offset:64
	v_fmac_f32_e32 v62, v58, v58
	s_waitcnt vmcnt(16)
	v_pk_add_f32 v[54:55], v[54:55], v[118:119]
	v_cvt_pk_bf16_f32 v58, v58, v59
	v_cvt_pk_bf16_f32 v59, v60, v61
	v_mov_b32_e32 v234, v58
	v_mov_b32_e32 v235, v59
	v_pk_add_f32 v[56:57], v[56:57], v[120:121]
	v_mul_f32_e32 v58, v55, v55
	global_store_dwordx4 v[122:123], v[54:57], off offset:512
	v_fmac_f32_e32 v58, v54, v54
	s_waitcnt vmcnt(17)
	v_pk_add_f32 v[50:51], v[50:51], v[114:115]
	v_cvt_pk_bf16_f32 v54, v54, v55
	v_fmac_f32_e32 v62, v60, v60
	v_cvt_pk_bf16_f32 v55, v56, v57
	v_mov_b32_e32 v236, v54
	v_mov_b32_e32 v237, v55
	v_mul_f32_e32 v54, v51, v51
	v_fmac_f32_e32 v62, v61, v61
	v_fmac_f32_e32 v58, v56, v56
	v_pk_add_f32 v[52:53], v[52:53], v[116:117]
	v_fmac_f32_e32 v54, v50, v50
	v_add_f32_e32 v62, v126, v62
	v_fmac_f32_e32 v58, v57, v57
	v_fmac_f32_e32 v54, v52, v52
	v_add_f32_e32 v58, v62, v58
	v_fmac_f32_e32 v54, v53, v53
	global_store_dwordx4 v[122:123], v[50:53], off offset:576
	v_add_f32_e32 v54, v58, v54
	s_nop 0
	v_cvt_pk_bf16_f32 v50, v50, v51
	v_cvt_pk_bf16_f32 v51, v52, v53
	v_mov_b32_e32 v238, v50
	v_mov_b32_e32 v239, v51
	v_lshl_add_u64 v[230:231], v[124:125], 0, v[228:229]
	s_waitcnt lgkmcnt(0)
	s_nop 1
	v_permlane16_swap_b32_e32 v232, v234
	v_permlane16_swap_b32_e32 v233, v235
	v_permlane16_swap_b32_e32 v236, v238
	v_permlane16_swap_b32_e32 v237, v239
	global_store_dwordx4 v[230:231], v[232:235], off
	global_store_dwordx4 v[230:231], v[236:239], off offset:256
	ds_bpermute_b32 v50, v182, v54
	s_waitcnt lgkmcnt(0)
	v_add_f32_e32 v50, v54, v50
	ds_bpermute_b32 v51, v146, v50
	s_and_saveexec_b64 s[18:19], s[42:43]
	s_cbranch_execz .LBB0_117
	s_waitcnt lgkmcnt(0)
	v_add_f32_e32 v50, v50, v51
	ds_write_b32 v0, v50 offset:2048
; DI unsigned cvt_pk(float lo, float hi) { unsigned r; asm("v_cvt_pk_bf16_f32 %0, %1, %2" : "=v"(r) : "v"(lo), "v"(hi)); return r; }
;   DI void operator()(LAS unsigned char* lds, f32x4 (&acc)[2][2][4][2], int pm, int pn, int wr, int wc, int fr, int fq) const {
;     ...
;       for (int m = 0; m < 4; ++m) {
;         const size_t off0 = base0 + (size_t)(ai * HALF + m * 16) * DM;
;         float* op = hout + off0; bf16_t* bp = hb + off0;
;         float q = 0.f;
; #pragma unroll
;         for (int bj = 0; bj < 2; ++bj)
; #pragma unroll
;           for (int n = 0; n < 2; ++n) {
;             const f32x4 o = rv[m][bj][n] + acc[ai][bj][m][n];
;             *(f32x4*)(op + bj * HALF + n * 16) = o;
;             q += o[0] * o[0] + o[1] * o[1] + o[2] * o[2] + o[3] * o[3];
;             u32x2 w; w.x = cvt_pk(o[0], o[1]); w.y = cvt_pk(o[2], o[3]);
;             *(u32x2*)(bp + bj * HALF + n * 16) = w;
;           }
;         q += __shfl_xor(q, 16); q += __shfl_xor(q, 32);
;         if (fq == 0) red[(ai * HALF + wr * 64 + m * 16 + fr) * 4 + wc] = q;
;       }
.LBB0_117:
	s_or_b64 exec, exec, s[18:19]
	s_waitcnt vmcnt(19)
	v_pk_add_f32 v[46:47], v[46:47], v[110:111]
	s_mov_b64 s[18:19], 0x90000
	v_mul_f32_e32 v54, v47, v47
	s_waitcnt lgkmcnt(0)
	v_lshl_add_u64 v[50:51], v[178:179], 0, s[18:19]
	v_pk_add_f32 v[48:49], v[48:49], v[112:113]
	v_fmac_f32_e32 v54, v46, v46
	global_store_dwordx4 v[50:51], v[46:49], off
	v_fmac_f32_e32 v54, v48, v48
	v_fmac_f32_e32 v54, v49, v49
	v_cvt_pk_bf16_f32 v46, v46, v47
	v_cvt_pk_bf16_f32 v47, v48, v49
	v_add_co_u32_e32 v48, vcc, s63, v180
	s_waitcnt vmcnt(19)
	v_pk_add_f32 v[42:43], v[42:43], v[106:107]
	v_addc_co_u32_e32 v49, vcc, 0, v181, vcc
	s_mov_b64 s[18:19], 0x48000
	v_mov_b32_e32 v240, v46
	v_mov_b32_e32 v241, v47
	v_pk_add_f32 v[44:45], v[44:45], v[108:109]
	v_mul_f32_e32 v46, v43, v43
	v_lshl_add_u64 v[52:53], v[180:181], 0, s[18:19]
	global_store_dwordx4 v[50:51], v[42:45], off offset:64
	v_fmac_f32_e32 v46, v42, v42
	s_waitcnt vmcnt(20)
	v_pk_add_f32 v[38:39], v[38:39], v[102:103]
	v_cvt_pk_bf16_f32 v42, v42, v43
	v_cvt_pk_bf16_f32 v43, v44, v45
	v_mov_b32_e32 v242, v42
	v_mov_b32_e32 v243, v43
	v_mul_f32_e32 v42, v39, v39
	v_fmac_f32_e32 v46, v44, v44
	v_pk_add_f32 v[40:41], v[40:41], v[104:105]
	v_fmac_f32_e32 v42, v38, v38
	v_fmac_f32_e32 v46, v45, v45
	v_fmac_f32_e32 v42, v40, v40
	v_add_f32_e32 v46, v54, v46
	v_fmac_f32_e32 v42, v41, v41
	v_add_f32_e32 v46, v46, v42
	s_waitcnt vmcnt(20)
	v_pk_add_f32 v[42:43], v[34:35], v[98:99]
	v_pk_add_f32 v[44:45], v[36:37], v[100:101]
	v_mul_f32_e32 v34, v43, v43
	v_fmac_f32_e32 v34, v42, v42
	v_fmac_f32_e32 v34, v44, v44
	v_fmac_f32_e32 v34, v45, v45
	v_add_f32_e32 v36, v46, v34
	ds_bpermute_b32 v37, v182, v36
	v_cvt_pk_bf16_f32 v34, v38, v39
	global_store_dwordx4 v[50:51], v[38:41], off offset:512
	v_cvt_pk_bf16_f32 v35, v40, v41
	v_mov_b32_e32 v244, v34
	v_mov_b32_e32 v245, v35
	s_waitcnt lgkmcnt(0)
	v_add_f32_e32 v34, v36, v37
	ds_bpermute_b32 v35, v146, v34
	global_store_dwordx4 v[50:51], v[42:45], off offset:576
	v_cvt_pk_bf16_f32 v36, v42, v43
	v_cvt_pk_bf16_f32 v37, v44, v45
	v_mov_b32_e32 v246, v36
	v_mov_b32_e32 v247, v37
	v_lshl_add_u64 v[230:231], v[52:53], 0, v[228:229]
	s_waitcnt lgkmcnt(0)
	s_nop 1
	v_permlane16_swap_b32_e32 v240, v242
	v_permlane16_swap_b32_e32 v241, v243
	v_permlane16_swap_b32_e32 v244, v246
	v_permlane16_swap_b32_e32 v245, v247
	global_store_dwordx4 v[230:231], v[240:243], off
	global_store_dwordx4 v[230:231], v[244:247], off offset:256
	s_and_saveexec_b64 s[18:19], s[42:43]
	s_cbranch_execz .LBB0_119
	s_waitcnt lgkmcnt(0)
	v_add_f32_e32 v34, v34, v35
	ds_write_b32 v0, v34 offset:2304
; DI unsigned cvt_pk(float lo, float hi) { unsigned r; asm("v_cvt_pk_bf16_f32 %0, %1, %2" : "=v"(r) : "v"(lo), "v"(hi)); return r; }
;   DI void operator()(LAS unsigned char* lds, f32x4 (&acc)[2][2][4][2], int pm, int pn, int wr, int wc, int fr, int fq) const {
;     ...
;       for (int m = 0; m < 4; ++m) {
;         const size_t off0 = base0 + (size_t)(ai * HALF + m * 16) * DM;
;         float* op = hout + off0; bf16_t* bp = hb + off0;
;         float q = 0.f;
; #pragma unroll
;         for (int bj = 0; bj < 2; ++bj)
; #pragma unroll
;           for (int n = 0; n < 2; ++n) {
;             const f32x4 o = rv[m][bj][n] + acc[ai][bj][m][n];
;             *(f32x4*)(op + bj * HALF + n * 16) = o;
;             q += o[0] * o[0] + o[1] * o[1] + o[2] * o[2] + o[3] * o[3];
;             u32x2 w; w.x = cvt_pk(o[0], o[1]); w.y = cvt_pk(o[2], o[3]);
;             *(u32x2*)(bp + bj * HALF + n * 16) = w;
;           }
;         q += __shfl_xor(q, 16); q += __shfl_xor(q, 32);
;         if (fq == 0) red[(ai * HALF + wr * 64 + m * 16 + fr) * 4 + wc] = q;
;       }
.LBB0_119:
	s_or_b64 exec, exec, s[18:19]
	s_mov_b64 s[18:19], 0xa0000
	s_waitcnt vmcnt(23)
	v_pk_add_f32 v[30:31], v[30:31], v[94:95]
	s_waitcnt lgkmcnt(0)
	v_lshl_add_u64 v[34:35], v[178:179], 0, s[18:19]
	s_mov_b64 s[18:19], 0x50000
	v_mul_f32_e32 v38, v31, v31
	v_lshl_add_u64 v[36:37], v[180:181], 0, s[18:19]
	v_pk_add_f32 v[32:33], v[32:33], v[96:97]
	v_fmac_f32_e32 v38, v30, v30
	s_mov_b32 s18, 0x50000
	global_store_dwordx4 v[34:35], v[30:33], off
	v_fmac_f32_e32 v38, v32, v32
	v_fmac_f32_e32 v38, v33, v33
	v_cvt_pk_bf16_f32 v30, v30, v31
	v_cvt_pk_bf16_f32 v31, v32, v33
	v_add_co_u32_e32 v32, vcc, s18, v180
	s_waitcnt vmcnt(23)
	v_pk_add_f32 v[26:27], v[26:27], v[90:91]
	v_addc_co_u32_e32 v33, vcc, 0, v181, vcc
	v_mov_b32_e32 v232, v30
	v_mov_b32_e32 v233, v31
	v_pk_add_f32 v[28:29], v[28:29], v[92:93]
	v_mul_f32_e32 v30, v27, v27
	global_store_dwordx4 v[34:35], v[26:29], off offset:64
	v_fmac_f32_e32 v30, v26, v26
	s_waitcnt vmcnt(24)
	v_pk_add_f32 v[22:23], v[22:23], v[86:87]
	v_cvt_pk_bf16_f32 v26, v26, v27
	v_cvt_pk_bf16_f32 v27, v28, v29
	v_mov_b32_e32 v234, v26
	v_mov_b32_e32 v235, v27
	v_mul_f32_e32 v26, v23, v23
	v_fmac_f32_e32 v30, v28, v28
	v_pk_add_f32 v[24:25], v[24:25], v[88:89]
	v_fmac_f32_e32 v26, v22, v22
	v_fmac_f32_e32 v30, v29, v29
	v_fmac_f32_e32 v26, v24, v24
	v_add_f32_e32 v30, v38, v30
	v_fmac_f32_e32 v26, v25, v25
	v_add_f32_e32 v30, v30, v26
	s_waitcnt vmcnt(24)
	v_pk_add_f32 v[26:27], v[18:19], v[78:79]
	v_pk_add_f32 v[28:29], v[20:21], v[80:81]
	v_mul_f32_e32 v18, v27, v27
	v_fmac_f32_e32 v18, v26, v26
	v_fmac_f32_e32 v18, v28, v28
	v_fmac_f32_e32 v18, v29, v29
	v_add_f32_e32 v20, v30, v18
	ds_bpermute_b32 v21, v182, v20
	v_cvt_pk_bf16_f32 v18, v22, v23
	global_store_dwordx4 v[34:35], v[22:25], off offset:512
	v_cvt_pk_bf16_f32 v19, v24, v25
	v_mov_b32_e32 v236, v18
	v_mov_b32_e32 v237, v19
	s_waitcnt lgkmcnt(0)
	v_add_f32_e32 v18, v20, v21
	ds_bpermute_b32 v19, v146, v18
	global_store_dwordx4 v[34:35], v[26:29], off offset:576
	v_cvt_pk_bf16_f32 v20, v26, v27
	v_cvt_pk_bf16_f32 v21, v28, v29
	v_mov_b32_e32 v238, v20
	v_mov_b32_e32 v239, v21
	v_lshl_add_u64 v[230:231], v[36:37], 0, v[228:229]
	s_waitcnt lgkmcnt(0)
	s_nop 1
	v_permlane16_swap_b32_e32 v232, v234
	v_permlane16_swap_b32_e32 v233, v235
	v_permlane16_swap_b32_e32 v236, v238
	v_permlane16_swap_b32_e32 v237, v239
	global_store_dwordx4 v[230:231], v[232:235], off
	global_store_dwordx4 v[230:231], v[236:239], off offset:256
	s_and_saveexec_b64 s[18:19], s[42:43]
	s_cbranch_execz .LBB0_121
	s_waitcnt lgkmcnt(0)
	v_add_f32_e32 v18, v18, v19
	ds_write_b32 v0, v18 offset:2560
.LBB0_121:
	s_or_b64 exec, exec, s[18:19]
	s_waitcnt vmcnt(27)
	v_pk_add_f32 v[14:15], v[14:15], v[82:83]
	s_mov_b64 s[18:19], 0xb0000
	v_mul_f32_e32 v22, v15, v15
	s_waitcnt lgkmcnt(0)
	v_lshl_add_u64 v[18:19], v[178:179], 0, s[18:19]
	v_pk_add_f32 v[16:17], v[16:17], v[84:85]
	v_fmac_f32_e32 v22, v14, v14
	global_store_dwordx4 v[18:19], v[14:17], off
	v_fmac_f32_e32 v22, v16, v16
	v_fmac_f32_e32 v22, v17, v17
	v_cvt_pk_bf16_f32 v14, v14, v15
	v_cvt_pk_bf16_f32 v15, v16, v17
	v_add_co_u32_e32 v16, vcc, s72, v180
	s_waitcnt vmcnt(27)
	v_pk_add_f32 v[10:11], v[10:11], v[74:75]
	v_addc_co_u32_e32 v17, vcc, 0, v181, vcc
	s_mov_b64 s[18:19], 0x58000
	v_mov_b32_e32 v240, v14
	v_mov_b32_e32 v241, v15
	v_pk_add_f32 v[12:13], v[12:13], v[76:77]
	v_mul_f32_e32 v14, v11, v11
	v_lshl_add_u64 v[20:21], v[180:181], 0, s[18:19]
	global_store_dwordx4 v[18:19], v[10:13], off offset:64
	v_fmac_f32_e32 v14, v10, v10
	s_waitcnt vmcnt(28)
	v_pk_add_f32 v[6:7], v[6:7], v[70:71]
	v_cvt_pk_bf16_f32 v10, v10, v11
	v_cvt_pk_bf16_f32 v11, v12, v13
	v_mov_b32_e32 v242, v10
	v_mov_b32_e32 v243, v11
	v_mul_f32_e32 v10, v7, v7
	v_fmac_f32_e32 v14, v12, v12
	v_pk_add_f32 v[8:9], v[8:9], v[72:73]
	v_fmac_f32_e32 v10, v6, v6
	v_fmac_f32_e32 v14, v13, v13
	v_fmac_f32_e32 v10, v8, v8
	v_add_f32_e32 v14, v22, v14
	v_fmac_f32_e32 v10, v9, v9
	v_add_f32_e32 v14, v14, v10
	s_waitcnt vmcnt(28)
	v_pk_add_f32 v[10:11], v[2:3], v[66:67]
	v_pk_add_f32 v[12:13], v[4:5], v[68:69]
	v_mul_f32_e32 v2, v11, v11
	v_fmac_f32_e32 v2, v10, v10
	v_fmac_f32_e32 v2, v12, v12
	v_fmac_f32_e32 v2, v13, v13
	v_add_f32_e32 v4, v14, v2
	ds_bpermute_b32 v5, v182, v4
	v_cvt_pk_bf16_f32 v2, v6, v7
	global_store_dwordx4 v[18:19], v[6:9], off offset:512
	v_cvt_pk_bf16_f32 v3, v8, v9
	v_mov_b32_e32 v244, v2
	v_mov_b32_e32 v245, v3
	s_waitcnt lgkmcnt(0)
	v_add_f32_e32 v2, v4, v5
	ds_bpermute_b32 v3, v146, v2
	global_store_dwordx4 v[18:19], v[10:13], off offset:576
	v_cvt_pk_bf16_f32 v4, v10, v11
	v_cvt_pk_bf16_f32 v5, v12, v13
	v_mov_b32_e32 v246, v4
	v_mov_b32_e32 v247, v5
	v_lshl_add_u64 v[230:231], v[20:21], 0, v[228:229]
	s_waitcnt lgkmcnt(0)
	s_nop 1
	v_permlane16_swap_b32_e32 v240, v242
	v_permlane16_swap_b32_e32 v241, v243
	v_permlane16_swap_b32_e32 v244, v246
	v_permlane16_swap_b32_e32 v245, v247
	global_store_dwordx4 v[230:231], v[240:243], off
	global_store_dwordx4 v[230:231], v[244:247], off offset:256
	s_and_saveexec_b64 s[18:19], s[42:43]
	s_cbranch_execz .LBB0_123
	s_waitcnt lgkmcnt(0)
	v_add_f32_e32 v2, v2, v3
	ds_write_b32 v0, v2 offset:2816

; #define LAS __attribute__((address_space(3)))
; DI unsigned cvt_pk(float lo, float hi) { unsigned r; asm("v_cvt_pk_bf16_f32 %0, %1, %2" : "=v"(r) : "v"(lo), "v"(hi)); return r; }
; #define EPI_FENCE asm volatile("" ::: "memory")
;   DI void operator()(LAS unsigned char* lds, f32x4 (&acc)[2][2][4][2], int pm, int pn, int wr, int wc, int fr, int fq) const {
;     const size_t base0 = (size_t)(pm * BM + wr * 64 + fr) * DM + pn * BM + wc * 32 + fq * 4;
;     LAS float* red = (LAS float*)(lds + 131072);
; #pragma unroll
;     for (int ai = 0; ai < 2; ++ai) {
;       f32x4 rv[4][2][2];
; #pragma unroll
;       for (int m = 0; m < 4; ++m)
; #pragma unroll
;         for (int bj = 0; bj < 2; ++bj)
; #pragma unroll
;           for (int n = 0; n < 2; ++n) rv[m][bj][n] = *(const f32x4*)(resid + base0 + (size_t)(ai * HALF + m * 16) * DM + bj * HALF + n * 16);
;       EPI_FENCE;
; #pragma unroll
;       for (int m = 0; m < 4; ++m) {
;         const size_t off0 = base0 + (size_t)(ai * HALF + m * 16) * DM;
;         float* op = hout + off0; bf16_t* bp = hb + off0;
;         float q = 0.f;
; #pragma unroll
;         for (int bj = 0; bj < 2; ++bj)
; #pragma unroll
;           for (int n = 0; n < 2; ++n) {
;             const f32x4 o = rv[m][bj][n] + acc[ai][bj][m][n];
;             *(f32x4*)(op + bj * HALF + n * 16) = o;
;             q += o[0] * o[0] + o[1] * o[1] + o[2] * o[2] + o[3] * o[3];
;             u32x2 w; w.x = cvt_pk(o[0], o[1]); w.y = cvt_pk(o[2], o[3]);
;             *(u32x2*)(bp + bj * HALF + n * 16) = w;
;           }
;         q += __shfl_xor(q, 16); q += __shfl_xor(q, 32);
;         if (fq == 0) red[(ai * HALF + wr * 64 + m * 16 + fr) * 4 + wc] = q;
;       }
.LBB0_512:
	s_or_b64 exec, exec, s[42:43]
	v_bfe_u32 v228, v220, 4, 1
	v_mul_u32_u24_e32 v228, 24, v228
	v_mov_b32_e32 v229, 0
	v_add_u32_e32 v82, s36, v218
	v_or_b32_e32 v82, v82, v213
	v_ashrrev_i32_e32 v83, 31, v82
	v_lshlrev_b64 v[82:83], 10, v[82:83]
	v_lshlrev_b32_e32 v84, 5, v210
	v_lshl_add_u64 v[178:179], v[82:83], 0, s[18:19]
	v_lshlrev_b32_e32 v82, 2, v212
	v_or3_b32 v178, v178, v84, v82
	v_lshlrev_b64 v[180:181], 2, v[178:179]
	v_lshl_add_u64 v[182:183], s[0:1], 0, v[180:181]
	global_load_dwordx4 v[186:189], v[182:183], off
	global_load_dwordx4 v[190:193], v[182:183], off offset:64
	global_load_dwordx4 v[194:197], v[182:183], off offset:512
	global_load_dwordx4 v[198:201], v[182:183], off offset:576
	s_mov_b32 s15, 0x10000
	v_add_co_u32_e32 v82, vcc, s15, v182
	s_mov_b32 s15, 0x20000
	s_nop 0
	v_addc_co_u32_e32 v83, vcc, 0, v183, vcc
	v_add_co_u32_e32 v84, vcc, s15, v182
	s_mov_b32 s15, 0x30000
	s_nop 0
	v_addc_co_u32_e32 v85, vcc, 0, v183, vcc
	v_add_co_u32_e32 v184, vcc, s15, v182
	v_lshl_add_u64 v[180:181], s[4:5], 0, v[180:181]
	s_nop 0
	v_addc_co_u32_e32 v185, vcc, 0, v183, vcc
	global_load_dwordx4 v[174:177], v[82:83], off
	global_load_dwordx4 v[170:173], v[82:83], off offset:64
	global_load_dwordx4 v[158:161], v[82:83], off offset:512
	global_load_dwordx4 v[154:157], v[82:83], off offset:576
	global_load_dwordx4 v[142:145], v[84:85], off
	global_load_dwordx4 v[130:133], v[84:85], off offset:64
	global_load_dwordx4 v[118:121], v[84:85], off offset:512
	global_load_dwordx4 v[114:117], v[84:85], off offset:576
	global_load_dwordx4 v[110:113], v[184:185], off
	global_load_dwordx4 v[98:101], v[184:185], off offset:64
	global_load_dwordx4 v[86:89], v[184:185], off offset:512
	s_nop 0
	global_load_dwordx4 v[82:85], v[184:185], off offset:576
	v_and_b32_e32 v185, 64, v224
	v_xor_b32_e32 v184, 16, v224
	v_add_u32_e32 v185, 64, v185
	v_cmp_lt_i32_e32 vcc, v184, v185
	v_xor_b32_e32 v202, 32, v224
	s_add_i32 s15, 0, 0x20000
	v_cndmask_b32_e32 v184, v224, v184, vcc
	v_lshlrev_b32_e32 v184, 2, v184
	v_cmp_lt_i32_e32 vcc, v202, v185
	v_lshl_add_u32 v203, v210, 2, s15
	v_cmp_eq_u32_e64 s[42:43], 0, v212
	v_cndmask_b32_e32 v185, v224, v202, vcc
	v_lshl_add_u64 v[178:179], v[178:179], 1, s[58:59]
	v_lshl_add_u32 v0, v0, 4, v203
	s_waitcnt vmcnt(0)
	v_pk_add_f32 v[148:149], v[148:149], v[188:189]
	v_pk_add_f32 v[146:147], v[146:147], v[186:187]
	v_pk_add_f32 v[150:151], v[150:151], v[190:191]
	v_pk_add_f32 v[152:153], v[152:153], v[192:193]
	v_pk_add_f32 v[162:163], v[162:163], v[194:195]
	global_store_dwordx4 v[180:181], v[146:149], off
	v_mul_f32_e32 v192, v147, v147
	v_cvt_pk_bf16_f32 v186, v146, v147
	v_pk_add_f32 v[166:167], v[166:167], v[198:199]
	v_mul_f32_e32 v147, v151, v151
	v_mul_f32_e32 v193, v163, v163
	v_fmac_f32_e32 v192, v146, v146
	v_fmac_f32_e32 v147, v150, v150
	v_pk_add_f32 v[164:165], v[164:165], v[196:197]
	v_mul_f32_e32 v194, v167, v167
	v_fmac_f32_e32 v193, v162, v162
	v_fmac_f32_e32 v192, v148, v148
	v_fmac_f32_e32 v147, v152, v152
	v_pk_add_f32 v[168:169], v[168:169], v[200:201]
	v_fmac_f32_e32 v194, v166, v166
	v_fmac_f32_e32 v193, v164, v164
	v_fmac_f32_e32 v192, v149, v149
	v_fmac_f32_e32 v147, v153, v153
	v_fmac_f32_e32 v194, v168, v168
	v_fmac_f32_e32 v193, v165, v165
	v_add_f32_e32 v146, v192, v147
	v_fmac_f32_e32 v194, v169, v169
	v_add_f32_e32 v146, v146, v193
	v_add_f32_e32 v146, v146, v194
	ds_bpermute_b32 v147, v184, v146
	v_cvt_pk_bf16_f32 v187, v148, v149
	v_cvt_pk_bf16_f32 v188, v150, v151
	v_cvt_pk_bf16_f32 v189, v152, v153
	v_cvt_pk_bf16_f32 v190, v162, v163
	s_waitcnt lgkmcnt(0)
	v_add_f32_e32 v147, v146, v147
	v_lshlrev_b32_e32 v146, 2, v185
	ds_bpermute_b32 v148, v146, v147
	v_cvt_pk_bf16_f32 v191, v164, v165
	v_mov_b32_e32 v232, v186
	v_mov_b32_e32 v233, v187
	global_store_dwordx4 v[180:181], v[150:153], off offset:64
	v_mov_b32_e32 v234, v188
	v_mov_b32_e32 v235, v189
	global_store_dwordx4 v[180:181], v[162:165], off offset:512
	v_mov_b32_e32 v236, v190
	v_mov_b32_e32 v237, v191
	global_store_dwordx4 v[180:181], v[166:169], off offset:576
	v_cvt_pk_bf16_f32 v150, v166, v167
	v_cvt_pk_bf16_f32 v151, v168, v169
	v_mov_b32_e32 v238, v150
	v_mov_b32_e32 v239, v151
	v_lshl_add_u64 v[230:231], v[178:179], 0, v[228:229]
	s_waitcnt lgkmcnt(0)
	s_nop 1
	v_permlane16_swap_b32_e32 v232, v234
	v_permlane16_swap_b32_e32 v233, v235
	v_permlane16_swap_b32_e32 v236, v238
	v_permlane16_swap_b32_e32 v237, v239
	global_store_dwordx4 v[230:231], v[232:235], off
	global_store_dwordx4 v[230:231], v[236:239], off offset:256
	s_and_saveexec_b64 s[18:19], s[42:43]
	s_cbranch_execz .LBB0_514
	s_waitcnt lgkmcnt(0)
	v_add_f32_e32 v147, v147, v148
	ds_write_b32 v0, v147
; DI unsigned cvt_pk(float lo, float hi) { unsigned r; asm("v_cvt_pk_bf16_f32 %0, %1, %2" : "=v"(r) : "v"(lo), "v"(hi)); return r; }
;   DI void operator()(LAS unsigned char* lds, f32x4 (&acc)[2][2][4][2], int pm, int pn, int wr, int wc, int fr, int fq) const {
;     ...
;       for (int m = 0; m < 4; ++m) {
;         const size_t off0 = base0 + (size_t)(ai * HALF + m * 16) * DM;
;         float* op = hout + off0; bf16_t* bp = hb + off0;
;         float q = 0.f;
; #pragma unroll
;         for (int bj = 0; bj < 2; ++bj)
; #pragma unroll
;           for (int n = 0; n < 2; ++n) {
;             const f32x4 o = rv[m][bj][n] + acc[ai][bj][m][n];
;             *(f32x4*)(op + bj * HALF + n * 16) = o;
;             q += o[0] * o[0] + o[1] * o[1] + o[2] * o[2] + o[3] * o[3];
;             u32x2 w; w.x = cvt_pk(o[0], o[1]); w.y = cvt_pk(o[2], o[3]);
;             *(u32x2*)(bp + bj * HALF + n * 16) = w;
;           }
;         q += __shfl_xor(q, 16); q += __shfl_xor(q, 32);
;         if (fq == 0) red[(ai * HALF + wr * 64 + m * 16 + fr) * 4 + wc] = q;
;       }
.LBB0_514:
	s_or_b64 exec, exec, s[18:19]
	v_pk_add_f32 v[138:139], v[138:139], v[174:175]
	v_add_co_u32_e32 v152, vcc, 0x10000, v180
	v_mul_f32_e32 v147, v139, v139
	v_pk_add_f32 v[140:141], v[140:141], v[176:177]
	v_addc_co_u32_e32 v153, vcc, 0, v181, vcc
	v_fmac_f32_e32 v147, v138, v138
	global_store_dwordx4 v[152:153], v[138:141], off
	v_fmac_f32_e32 v147, v140, v140
	s_mov_b64 s[16:17], 0x10000
	v_cvt_pk_bf16_f32 v138, v138, v139
	v_cvt_pk_bf16_f32 v139, v140, v141
	v_add_co_u32_e32 v140, vcc, 0x8000, v178
	v_fmac_f32_e32 v147, v141, v141
	s_nop 0
	v_addc_co_u32_e32 v141, vcc, 0, v179, vcc
	v_pk_add_f32 v[126:127], v[126:127], v[170:171]
	s_waitcnt lgkmcnt(0)
	v_lshl_add_u64 v[148:149], v[180:181], 0, s[16:17]
	s_mov_b64 s[16:17], 0x8000
	v_mov_b32_e32 v240, v138
	v_mov_b32_e32 v241, v139
	v_pk_add_f32 v[128:129], v[128:129], v[172:173]
	v_mul_f32_e32 v138, v127, v127
	v_lshl_add_u64 v[150:151], v[178:179], 0, s[16:17]
	global_store_dwordx4 v[148:149], v[126:129], off offset:64
	v_fmac_f32_e32 v138, v126, v126
	v_fmac_f32_e32 v138, v128, v128
	v_cvt_pk_bf16_f32 v126, v126, v127
	v_cvt_pk_bf16_f32 v127, v128, v129
	v_mov_b32_e32 v242, v126
	v_mov_b32_e32 v243, v127
	v_pk_add_f32 v[126:127], v[134:135], v[158:159]
	v_fmac_f32_e32 v138, v129, v129
	v_mul_f32_e32 v134, v127, v127
	v_pk_add_f32 v[128:129], v[136:137], v[160:161]
	v_fmac_f32_e32 v134, v126, v126
	v_fmac_f32_e32 v134, v128, v128
	v_add_f32_e32 v138, v147, v138
	v_fmac_f32_e32 v134, v129, v129
	v_add_f32_e32 v138, v138, v134
	v_pk_add_f32 v[134:135], v[122:123], v[154:155]
	v_pk_add_f32 v[136:137], v[124:125], v[156:157]
	v_mul_f32_e32 v122, v135, v135
	v_fmac_f32_e32 v122, v134, v134
	v_fmac_f32_e32 v122, v136, v136
	v_fmac_f32_e32 v122, v137, v137
	v_add_f32_e32 v124, v138, v122
	ds_bpermute_b32 v125, v184, v124
	v_cvt_pk_bf16_f32 v122, v126, v127
	global_store_dwordx4 v[148:149], v[126:129], off offset:512
	v_cvt_pk_bf16_f32 v123, v128, v129
	v_mov_b32_e32 v244, v122
	v_mov_b32_e32 v245, v123
	s_waitcnt lgkmcnt(0)
	v_add_f32_e32 v122, v124, v125
	ds_bpermute_b32 v123, v146, v122
	global_store_dwordx4 v[148:149], v[134:137], off offset:576
	v_cvt_pk_bf16_f32 v124, v134, v135
	v_cvt_pk_bf16_f32 v125, v136, v137
	v_mov_b32_e32 v246, v124
	v_mov_b32_e32 v247, v125
	v_lshl_add_u64 v[230:231], v[150:151], 0, v[228:229]
	s_waitcnt lgkmcnt(0)
	s_nop 1
	v_permlane16_swap_b32_e32 v240, v242
	v_permlane16_swap_b32_e32 v241, v243
	v_permlane16_swap_b32_e32 v244, v246
	v_permlane16_swap_b32_e32 v245, v247
	global_store_dwordx4 v[230:231], v[240:243], off
	global_store_dwordx4 v[230:231], v[244:247], off offset:256
	s_and_saveexec_b64 s[18:19], s[42:43]
	s_cbranch_execz .LBB0_516
	s_waitcnt lgkmcnt(0)
	v_add_f32_e32 v122, v122, v123
	ds_write_b32 v0, v122 offset:256
.LBB0_516:
	s_or_b64 exec, exec, s[18:19]
	v_add_co_u32_e32 v126, vcc, 0x20000, v180
	v_pk_add_f32 v[108:109], v[108:109], v[144:145]
	v_pk_add_f32 v[106:107], v[106:107], v[142:143]
	v_addc_co_u32_e32 v127, vcc, 0, v181, vcc
	global_store_dwordx4 v[126:127], v[106:109], off
	v_mul_f32_e32 v126, v107, v107
	v_fmac_f32_e32 v126, v106, v106
	s_mov_b32 s15, 0x10000
	v_fmac_f32_e32 v126, v108, v108
	v_cvt_pk_bf16_f32 v106, v106, v107
	v_cvt_pk_bf16_f32 v107, v108, v109
	v_add_co_u32_e32 v108, vcc, s15, v178
	s_mov_b64 s[16:17], 0x20000
	v_fmac_f32_e32 v126, v109, v109
	v_addc_co_u32_e32 v109, vcc, 0, v179, vcc
	v_pk_add_f32 v[94:95], v[94:95], v[130:131]
	s_waitcnt lgkmcnt(0)
	v_lshl_add_u64 v[122:123], v[180:181], 0, s[16:17]
	s_mov_b64 s[16:17], 0x10000
	v_mov_b32_e32 v232, v106
	v_mov_b32_e32 v233, v107
	v_pk_add_f32 v[96:97], v[96:97], v[132:133]
	v_mul_f32_e32 v106, v95, v95
	v_lshl_add_u64 v[124:125], v[178:179], 0, s[16:17]
	global_store_dwordx4 v[122:123], v[94:97], off offset:64
	v_fmac_f32_e32 v106, v94, v94
	v_fmac_f32_e32 v106, v96, v96
	v_cvt_pk_bf16_f32 v94, v94, v95
	v_cvt_pk_bf16_f32 v95, v96, v97
	v_mov_b32_e32 v234, v94
	v_mov_b32_e32 v235, v95
	v_pk_add_f32 v[94:95], v[102:103], v[118:119]
	v_fmac_f32_e32 v106, v97, v97
	v_mul_f32_e32 v102, v95, v95
	v_pk_add_f32 v[96:97], v[104:105], v[120:121]
	v_fmac_f32_e32 v102, v94, v94
	v_fmac_f32_e32 v102, v96, v96
	v_add_f32_e32 v106, v126, v106
	v_fmac_f32_e32 v102, v97, v97
	v_add_f32_e32 v106, v106, v102
	v_pk_add_f32 v[102:103], v[90:91], v[114:115]
	v_pk_add_f32 v[104:105], v[92:93], v[116:117]
	v_mul_f32_e32 v90, v103, v103
	v_fmac_f32_e32 v90, v102, v102
	v_fmac_f32_e32 v90, v104, v104
	v_fmac_f32_e32 v90, v105, v105
	v_add_f32_e32 v92, v106, v90
	ds_bpermute_b32 v93, v184, v92
	v_cvt_pk_bf16_f32 v90, v94, v95
	global_store_dwordx4 v[122:123], v[94:97], off offset:512
	v_cvt_pk_bf16_f32 v91, v96, v97
	v_mov_b32_e32 v236, v90
	v_mov_b32_e32 v237, v91
	s_waitcnt lgkmcnt(0)
	v_add_f32_e32 v90, v92, v93
	ds_bpermute_b32 v91, v146, v90
	global_store_dwordx4 v[122:123], v[102:105], off offset:576
	v_cvt_pk_bf16_f32 v92, v102, v103
	v_cvt_pk_bf16_f32 v93, v104, v105
	v_mov_b32_e32 v238, v92
	v_mov_b32_e32 v239, v93
	v_lshl_add_u64 v[230:231], v[124:125], 0, v[228:229]
	s_waitcnt lgkmcnt(0)
	s_nop 1
	v_permlane16_swap_b32_e32 v232, v234
	v_permlane16_swap_b32_e32 v233, v235
	v_permlane16_swap_b32_e32 v236, v238
	v_permlane16_swap_b32_e32 v237, v239
	global_store_dwordx4 v[230:231], v[232:235], off
	global_store_dwordx4 v[230:231], v[236:239], off offset:256
	s_and_saveexec_b64 s[18:19], s[42:43]
	s_cbranch_execz .LBB0_518
	s_waitcnt lgkmcnt(0)
	v_add_f32_e32 v90, v90, v91
	ds_write_b32 v0, v90 offset:512
; DI unsigned cvt_pk(float lo, float hi) { unsigned r; asm("v_cvt_pk_bf16_f32 %0, %1, %2" : "=v"(r) : "v"(lo), "v"(hi)); return r; }
; #define EPI_FENCE asm volatile("" ::: "memory")
;   DI void operator()(LAS unsigned char* lds, f32x4 (&acc)[2][2][4][2], int pm, int pn, int wr, int wc, int fr, int fq) const {
;     ...
;       for (int m = 0; m < 4; ++m)
; #pragma unroll
;         for (int bj = 0; bj < 2; ++bj)
; #pragma unroll
;           for (int n = 0; n < 2; ++n) rv[m][bj][n] = *(const f32x4*)(resid + base0 + (size_t)(ai * HALF + m * 16) * DM + bj * HALF + n * 16);
;       EPI_FENCE;
; #pragma unroll
;       for (int m = 0; m < 4; ++m) {
;         const size_t off0 = base0 + (size_t)(ai * HALF + m * 16) * DM;
;         float* op = hout + off0; bf16_t* bp = hb + off0;
;         float q = 0.f;
; #pragma unroll
;         for (int bj = 0; bj < 2; ++bj)
; #pragma unroll
;           for (int n = 0; n < 2; ++n) {
;             const f32x4 o = rv[m][bj][n] + acc[ai][bj][m][n];
;             *(f32x4*)(op + bj * HALF + n * 16) = o;
;             q += o[0] * o[0] + o[1] * o[1] + o[2] * o[2] + o[3] * o[3];
;             u32x2 w; w.x = cvt_pk(o[0], o[1]); w.y = cvt_pk(o[2], o[3]);
;             *(u32x2*)(bp + bj * HALF + n * 16) = w;
;           }
;         q += __shfl_xor(q, 16); q += __shfl_xor(q, 32);
;         if (fq == 0) red[(ai * HALF + wr * 64 + m * 16 + fr) * 4 + wc] = q;
;       }
.LBB0_518:
	s_or_b64 exec, exec, s[18:19]
	v_add_co_u32_e32 v94, vcc, 0x30000, v180
	v_pk_add_f32 v[80:81], v[80:81], v[112:113]
	v_pk_add_f32 v[78:79], v[78:79], v[110:111]
	v_addc_co_u32_e32 v95, vcc, 0, v181, vcc
	global_store_dwordx4 v[94:95], v[78:81], off
	v_mul_f32_e32 v94, v79, v79
	v_fmac_f32_e32 v94, v78, v78
	s_mov_b32 s15, 0x18000
	v_fmac_f32_e32 v94, v80, v80
	v_cvt_pk_bf16_f32 v78, v78, v79
	v_cvt_pk_bf16_f32 v79, v80, v81
	v_add_co_u32_e32 v80, vcc, s15, v178
	s_mov_b64 s[16:17], 0x30000
	v_fmac_f32_e32 v94, v81, v81
	v_addc_co_u32_e32 v81, vcc, 0, v179, vcc
	v_pk_add_f32 v[70:71], v[70:71], v[98:99]
	s_waitcnt lgkmcnt(0)
	v_lshl_add_u64 v[90:91], v[180:181], 0, s[16:17]
	s_mov_b64 s[16:17], 0x18000
	v_mov_b32_e32 v240, v78
	v_mov_b32_e32 v241, v79
	v_pk_add_f32 v[72:73], v[72:73], v[100:101]
	v_mul_f32_e32 v78, v71, v71
	v_lshl_add_u64 v[92:93], v[178:179], 0, s[16:17]
	global_store_dwordx4 v[90:91], v[70:73], off offset:64
	v_fmac_f32_e32 v78, v70, v70
	v_fmac_f32_e32 v78, v72, v72
	v_cvt_pk_bf16_f32 v70, v70, v71
	v_cvt_pk_bf16_f32 v71, v72, v73
	v_mov_b32_e32 v242, v70
	v_mov_b32_e32 v243, v71
	v_pk_add_f32 v[70:71], v[74:75], v[86:87]
	v_fmac_f32_e32 v78, v73, v73
	v_mul_f32_e32 v74, v71, v71
	v_pk_add_f32 v[72:73], v[76:77], v[88:89]
	v_fmac_f32_e32 v74, v70, v70
	v_fmac_f32_e32 v74, v72, v72
	v_add_f32_e32 v78, v94, v78
	v_fmac_f32_e32 v74, v73, v73
	v_add_f32_e32 v78, v78, v74
	v_pk_add_f32 v[74:75], v[66:67], v[82:83]
	v_pk_add_f32 v[76:77], v[68:69], v[84:85]
	v_mul_f32_e32 v66, v75, v75
	v_fmac_f32_e32 v66, v74, v74
	v_fmac_f32_e32 v66, v76, v76
	v_fmac_f32_e32 v66, v77, v77
	v_add_f32_e32 v68, v78, v66
	ds_bpermute_b32 v69, v184, v68
	v_cvt_pk_bf16_f32 v66, v70, v71
	global_store_dwordx4 v[90:91], v[70:73], off offset:512
	v_cvt_pk_bf16_f32 v67, v72, v73
	v_mov_b32_e32 v244, v66
	v_mov_b32_e32 v245, v67
	s_waitcnt lgkmcnt(0)
	v_add_f32_e32 v66, v68, v69
	ds_bpermute_b32 v67, v146, v66
	global_store_dwordx4 v[90:91], v[74:77], off offset:576
	v_cvt_pk_bf16_f32 v68, v74, v75
	v_cvt_pk_bf16_f32 v69, v76, v77
	v_mov_b32_e32 v246, v68
	v_mov_b32_e32 v247, v69
	v_lshl_add_u64 v[230:231], v[92:93], 0, v[228:229]
	s_waitcnt lgkmcnt(0)
	s_nop 1
	v_permlane16_swap_b32_e32 v240, v242
	v_permlane16_swap_b32_e32 v241, v243
	v_permlane16_swap_b32_e32 v244, v246
	v_permlane16_swap_b32_e32 v245, v247
	global_store_dwordx4 v[230:231], v[240:243], off
	global_store_dwordx4 v[230:231], v[244:247], off offset:256
	s_and_saveexec_b64 s[18:19], s[42:43]
	s_cbranch_execz .LBB0_520
	s_waitcnt lgkmcnt(0)
	v_add_f32_e32 v66, v66, v67
	ds_write_b32 v0, v66 offset:768
.LBB0_520:
	s_or_b64 exec, exec, s[18:19]
	v_add_co_u32_e32 v66, vcc, 0x80000, v182
	s_mov_b32 s15, 0x80000
	s_waitcnt lgkmcnt(0)
	v_addc_co_u32_e32 v67, vcc, 0, v183, vcc
	global_load_dwordx4 v[124:127], v[66:67], off
	global_load_dwordx4 v[128:131], v[66:67], off offset:64
	global_load_dwordx4 v[118:121], v[66:67], off offset:512
	global_load_dwordx4 v[114:117], v[66:67], off offset:576
	v_add_co_u32_e32 v66, vcc, 0x90000, v182
	s_mov_b64 s[16:17], 0x80000
	s_nop 0
	v_addc_co_u32_e32 v67, vcc, 0, v183, vcc
	global_load_dwordx4 v[110:113], v[66:67], off
	global_load_dwordx4 v[106:109], v[66:67], off offset:64
	global_load_dwordx4 v[102:105], v[66:67], off offset:512
	global_load_dwordx4 v[98:101], v[66:67], off offset:576
	v_add_co_u32_e32 v66, vcc, 0xa0000, v182
	v_lshl_add_u64 v[132:133], v[180:181], 0, s[16:17]
	s_nop 0
	v_addc_co_u32_e32 v67, vcc, 0, v183, vcc
	global_load_dwordx4 v[94:97], v[66:67], off
	global_load_dwordx4 v[90:93], v[66:67], off offset:64
	global_load_dwordx4 v[86:89], v[66:67], off offset:512
	global_load_dwordx4 v[78:81], v[66:67], off offset:576
	v_add_co_u32_e32 v66, vcc, 0xb0000, v182
	s_mov_b64 s[16:17], 0x40000
	s_nop 0
	v_addc_co_u32_e32 v67, vcc, 0, v183, vcc
	global_load_dwordx4 v[82:85], v[66:67], off
	global_load_dwordx4 v[74:77], v[66:67], off offset:64
	global_load_dwordx4 v[70:73], v[66:67], off offset:512
	s_nop 0
	global_load_dwordx4 v[66:69], v[66:67], off offset:576
	v_lshl_add_u64 v[122:123], v[178:179], 0, s[16:17]
	s_waitcnt vmcnt(15)
	v_pk_add_f32 v[62:63], v[62:63], v[124:125]
	v_add_co_u32_e32 v124, vcc, s15, v180
	v_pk_add_f32 v[64:65], v[64:65], v[126:127]
	s_nop 0
	v_addc_co_u32_e32 v125, vcc, 0, v181, vcc
	global_store_dwordx4 v[124:125], v[62:65], off
	v_mul_f32_e32 v124, v63, v63
	v_fmac_f32_e32 v124, v62, v62
	s_mov_b32 s15, 0x40000
	v_fmac_f32_e32 v124, v64, v64
	v_cvt_pk_bf16_f32 v62, v62, v63
	v_cvt_pk_bf16_f32 v63, v64, v65
	v_add_co_u32_e32 v64, vcc, s15, v178
	v_fmac_f32_e32 v124, v65, v65
	s_nop 0
	v_addc_co_u32_e32 v65, vcc, 0, v179, vcc
	s_waitcnt vmcnt(15)
	v_pk_add_f32 v[58:59], v[58:59], v[128:129]
	v_mov_b32_e32 v232, v62
	v_mov_b32_e32 v233, v63
	v_pk_add_f32 v[60:61], v[60:61], v[130:131]
	v_mul_f32_e32 v62, v59, v59
	global_store_dwordx4 v[132:133], v[58:61], off offset:64
	v_fmac_f32_e32 v62, v58, v58
	s_waitcnt vmcnt(16)
	v_pk_add_f32 v[54:55], v[54:55], v[118:119]
	v_cvt_pk_bf16_f32 v58, v58, v59
	v_cvt_pk_bf16_f32 v59, v60, v61
	v_mov_b32_e32 v234, v58
	v_mov_b32_e32 v235, v59
	v_pk_add_f32 v[56:57], v[56:57], v[120:121]
	v_mul_f32_e32 v58, v55, v55
	global_store_dwordx4 v[132:133], v[54:57], off offset:512
	v_fmac_f32_e32 v58, v54, v54
	s_waitcnt vmcnt(17)
	v_pk_add_f32 v[50:51], v[50:51], v[114:115]
	v_cvt_pk_bf16_f32 v54, v54, v55
	v_fmac_f32_e32 v62, v60, v60
	v_cvt_pk_bf16_f32 v55, v56, v57
	v_mov_b32_e32 v236, v54
	v_mov_b32_e32 v237, v55
	v_mul_f32_e32 v54, v51, v51
	v_fmac_f32_e32 v62, v61, v61
	v_fmac_f32_e32 v58, v56, v56
	v_pk_add_f32 v[52:53], v[52:53], v[116:117]
	v_fmac_f32_e32 v54, v50, v50
	v_add_f32_e32 v62, v124, v62
	v_fmac_f32_e32 v58, v57, v57
	v_fmac_f32_e32 v54, v52, v52
	v_add_f32_e32 v58, v62, v58
	v_fmac_f32_e32 v54, v53, v53
	global_store_dwordx4 v[132:133], v[50:53], off offset:576
	v_add_f32_e32 v54, v58, v54
	s_nop 0
	v_cvt_pk_bf16_f32 v50, v50, v51
	v_cvt_pk_bf16_f32 v51, v52, v53
	v_mov_b32_e32 v238, v50
	v_mov_b32_e32 v239, v51
	v_lshl_add_u64 v[230:231], v[122:123], 0, v[228:229]
	s_waitcnt lgkmcnt(0)
	s_nop 1
	v_permlane16_swap_b32_e32 v232, v234
	v_permlane16_swap_b32_e32 v233, v235
	v_permlane16_swap_b32_e32 v236, v238
	v_permlane16_swap_b32_e32 v237, v239
	global_store_dwordx4 v[230:231], v[232:235], off
	global_store_dwordx4 v[230:231], v[236:239], off offset:256
	ds_bpermute_b32 v50, v184, v54
	s_waitcnt lgkmcnt(0)
	v_add_f32_e32 v50, v54, v50
	ds_bpermute_b32 v51, v146, v50
	s_and_saveexec_b64 s[18:19], s[42:43]
	s_cbranch_execz .LBB0_522
	s_waitcnt lgkmcnt(0)
	v_add_f32_e32 v50, v50, v51
	ds_write_b32 v0, v50 offset:2048
; DI unsigned cvt_pk(float lo, float hi) { unsigned r; asm("v_cvt_pk_bf16_f32 %0, %1, %2" : "=v"(r) : "v"(lo), "v"(hi)); return r; }
;   DI void operator()(LAS unsigned char* lds, f32x4 (&acc)[2][2][4][2], int pm, int pn, int wr, int wc, int fr, int fq) const {
;     ...
;       for (int m = 0; m < 4; ++m) {
;         const size_t off0 = base0 + (size_t)(ai * HALF + m * 16) * DM;
;         float* op = hout + off0; bf16_t* bp = hb + off0;
;         float q = 0.f;
; #pragma unroll
;         for (int bj = 0; bj < 2; ++bj)
; #pragma unroll
;           for (int n = 0; n < 2; ++n) {
;             const f32x4 o = rv[m][bj][n] + acc[ai][bj][m][n];
;             *(f32x4*)(op + bj * HALF + n * 16) = o;
;             q += o[0] * o[0] + o[1] * o[1] + o[2] * o[2] + o[3] * o[3];
;             u32x2 w; w.x = cvt_pk(o[0], o[1]); w.y = cvt_pk(o[2], o[3]);
;             *(u32x2*)(bp + bj * HALF + n * 16) = w;
;           }
;         q += __shfl_xor(q, 16); q += __shfl_xor(q, 32);
;         if (fq == 0) red[(ai * HALF + wr * 64 + m * 16 + fr) * 4 + wc] = q;
;       }
.LBB0_522:
	s_or_b64 exec, exec, s[18:19]
	v_add_co_u32_e32 v54, vcc, 0x90000, v180
	s_waitcnt vmcnt(19)
	v_pk_add_f32 v[48:49], v[48:49], v[112:113]
	v_pk_add_f32 v[46:47], v[46:47], v[110:111]
	v_addc_co_u32_e32 v55, vcc, 0, v181, vcc
	global_store_dwordx4 v[54:55], v[46:49], off
	v_mul_f32_e32 v54, v47, v47
	v_fmac_f32_e32 v54, v46, v46
	v_fmac_f32_e32 v54, v48, v48
	v_cvt_pk_bf16_f32 v46, v46, v47
	v_cvt_pk_bf16_f32 v47, v48, v49
	v_add_co_u32_e32 v48, vcc, 0x48000, v178
	s_mov_b64 s[16:17], 0x90000
	v_fmac_f32_e32 v54, v49, v49
	v_addc_co_u32_e32 v49, vcc, 0, v179, vcc
	s_waitcnt vmcnt(19)
	v_pk_add_f32 v[42:43], v[42:43], v[106:107]
	s_waitcnt lgkmcnt(0)
	v_lshl_add_u64 v[50:51], v[180:181], 0, s[16:17]
	s_mov_b64 s[16:17], 0x48000
	v_mov_b32_e32 v240, v46
	v_mov_b32_e32 v241, v47
	v_pk_add_f32 v[44:45], v[44:45], v[108:109]
	v_mul_f32_e32 v46, v43, v43
	v_lshl_add_u64 v[52:53], v[178:179], 0, s[16:17]
	global_store_dwordx4 v[50:51], v[42:45], off offset:64
	v_fmac_f32_e32 v46, v42, v42
	s_waitcnt vmcnt(20)
	v_pk_add_f32 v[38:39], v[38:39], v[102:103]
	v_cvt_pk_bf16_f32 v42, v42, v43
	v_cvt_pk_bf16_f32 v43, v44, v45
	v_mov_b32_e32 v242, v42
	v_mov_b32_e32 v243, v43
	v_mul_f32_e32 v42, v39, v39
	v_fmac_f32_e32 v46, v44, v44
	v_pk_add_f32 v[40:41], v[40:41], v[104:105]
	v_fmac_f32_e32 v42, v38, v38
	v_fmac_f32_e32 v46, v45, v45
	v_fmac_f32_e32 v42, v40, v40
	v_add_f32_e32 v46, v54, v46
	v_fmac_f32_e32 v42, v41, v41
	v_add_f32_e32 v46, v46, v42
	s_waitcnt vmcnt(20)
	v_pk_add_f32 v[42:43], v[34:35], v[98:99]
	v_pk_add_f32 v[44:45], v[36:37], v[100:101]
	v_mul_f32_e32 v34, v43, v43
	v_fmac_f32_e32 v34, v42, v42
	v_fmac_f32_e32 v34, v44, v44
	v_fmac_f32_e32 v34, v45, v45
	v_add_f32_e32 v36, v46, v34
	ds_bpermute_b32 v37, v184, v36
	v_cvt_pk_bf16_f32 v34, v38, v39
	global_store_dwordx4 v[50:51], v[38:41], off offset:512
	v_cvt_pk_bf16_f32 v35, v40, v41
	v_mov_b32_e32 v244, v34
	v_mov_b32_e32 v245, v35
	s_waitcnt lgkmcnt(0)
	v_add_f32_e32 v34, v36, v37
	ds_bpermute_b32 v35, v146, v34
	global_store_dwordx4 v[50:51], v[42:45], off offset:576
	v_cvt_pk_bf16_f32 v36, v42, v43
	v_cvt_pk_bf16_f32 v37, v44, v45
	v_mov_b32_e32 v246, v36
	v_mov_b32_e32 v247, v37
	v_lshl_add_u64 v[230:231], v[52:53], 0, v[228:229]
	s_waitcnt lgkmcnt(0)
	s_nop 1
	v_permlane16_swap_b32_e32 v240, v242
	v_permlane16_swap_b32_e32 v241, v243
	v_permlane16_swap_b32_e32 v244, v246
	v_permlane16_swap_b32_e32 v245, v247
	global_store_dwordx4 v[230:231], v[240:243], off
	global_store_dwordx4 v[230:231], v[244:247], off offset:256
	s_and_saveexec_b64 s[18:19], s[42:43]
	s_cbranch_execz .LBB0_524
	s_waitcnt lgkmcnt(0)
	v_add_f32_e32 v34, v34, v35
	ds_write_b32 v0, v34 offset:2304
; DI unsigned cvt_pk(float lo, float hi) { unsigned r; asm("v_cvt_pk_bf16_f32 %0, %1, %2" : "=v"(r) : "v"(lo), "v"(hi)); return r; }
;   DI void operator()(LAS unsigned char* lds, f32x4 (&acc)[2][2][4][2], int pm, int pn, int wr, int wc, int fr, int fq) const {
;     ...
;       for (int m = 0; m < 4; ++m) {
;         const size_t off0 = base0 + (size_t)(ai * HALF + m * 16) * DM;
;         float* op = hout + off0; bf16_t* bp = hb + off0;
;         float q = 0.f;
; #pragma unroll
;         for (int bj = 0; bj < 2; ++bj)
; #pragma unroll
;           for (int n = 0; n < 2; ++n) {
;             const f32x4 o = rv[m][bj][n] + acc[ai][bj][m][n];
;             *(f32x4*)(op + bj * HALF + n * 16) = o;
;             q += o[0] * o[0] + o[1] * o[1] + o[2] * o[2] + o[3] * o[3];
;             u32x2 w; w.x = cvt_pk(o[0], o[1]); w.y = cvt_pk(o[2], o[3]);
;             *(u32x2*)(bp + bj * HALF + n * 16) = w;
;           }
;         q += __shfl_xor(q, 16); q += __shfl_xor(q, 32);
;         if (fq == 0) red[(ai * HALF + wr * 64 + m * 16 + fr) * 4 + wc] = q;
;       }
.LBB0_524:
	s_or_b64 exec, exec, s[18:19]
	v_add_co_u32_e32 v38, vcc, 0xa0000, v180
	s_waitcnt vmcnt(23)
	v_pk_add_f32 v[32:33], v[32:33], v[96:97]
	v_pk_add_f32 v[30:31], v[30:31], v[94:95]
	v_addc_co_u32_e32 v39, vcc, 0, v181, vcc
	global_store_dwordx4 v[38:39], v[30:33], off
	v_mul_f32_e32 v38, v31, v31
	v_fmac_f32_e32 v38, v30, v30
	v_fmac_f32_e32 v38, v32, v32
	v_cvt_pk_bf16_f32 v30, v30, v31
	v_cvt_pk_bf16_f32 v31, v32, v33
	v_add_co_u32_e32 v32, vcc, 0x50000, v178
	s_mov_b64 s[16:17], 0xa0000
	v_fmac_f32_e32 v38, v33, v33
	v_addc_co_u32_e32 v33, vcc, 0, v179, vcc
	s_waitcnt vmcnt(23)
	v_pk_add_f32 v[26:27], v[26:27], v[90:91]
	s_waitcnt lgkmcnt(0)
	v_lshl_add_u64 v[34:35], v[180:181], 0, s[16:17]
	s_mov_b64 s[16:17], 0x50000
	v_mov_b32_e32 v232, v30
	v_mov_b32_e32 v233, v31
	v_pk_add_f32 v[28:29], v[28:29], v[92:93]
	v_mul_f32_e32 v30, v27, v27
	v_lshl_add_u64 v[36:37], v[178:179], 0, s[16:17]
	global_store_dwordx4 v[34:35], v[26:29], off offset:64
	v_fmac_f32_e32 v30, v26, v26
	s_waitcnt vmcnt(24)
	v_pk_add_f32 v[22:23], v[22:23], v[86:87]
	v_cvt_pk_bf16_f32 v26, v26, v27
	v_cvt_pk_bf16_f32 v27, v28, v29
	v_mov_b32_e32 v234, v26
	v_mov_b32_e32 v235, v27
	v_mul_f32_e32 v26, v23, v23
	v_fmac_f32_e32 v30, v28, v28
	v_pk_add_f32 v[24:25], v[24:25], v[88:89]
	v_fmac_f32_e32 v26, v22, v22
	v_fmac_f32_e32 v30, v29, v29
	v_fmac_f32_e32 v26, v24, v24
	v_add_f32_e32 v30, v38, v30
	v_fmac_f32_e32 v26, v25, v25
	v_add_f32_e32 v30, v30, v26
	s_waitcnt vmcnt(24)
	v_pk_add_f32 v[26:27], v[18:19], v[78:79]
	v_pk_add_f32 v[28:29], v[20:21], v[80:81]
	v_mul_f32_e32 v18, v27, v27
	v_fmac_f32_e32 v18, v26, v26
	v_fmac_f32_e32 v18, v28, v28
	v_fmac_f32_e32 v18, v29, v29
	v_add_f32_e32 v20, v30, v18
	ds_bpermute_b32 v21, v184, v20
	v_cvt_pk_bf16_f32 v18, v22, v23
	global_store_dwordx4 v[34:35], v[22:25], off offset:512
	v_cvt_pk_bf16_f32 v19, v24, v25
	v_mov_b32_e32 v236, v18
	v_mov_b32_e32 v237, v19
	s_waitcnt lgkmcnt(0)
	v_add_f32_e32 v18, v20, v21
	ds_bpermute_b32 v19, v146, v18
	global_store_dwordx4 v[34:35], v[26:29], off offset:576
	v_cvt_pk_bf16_f32 v20, v26, v27
	v_cvt_pk_bf16_f32 v21, v28, v29
	v_mov_b32_e32 v238, v20
	v_mov_b32_e32 v239, v21
	v_lshl_add_u64 v[230:231], v[36:37], 0, v[228:229]
	s_waitcnt lgkmcnt(0)
	s_nop 1
	v_permlane16_swap_b32_e32 v232, v234
	v_permlane16_swap_b32_e32 v233, v235
	v_permlane16_swap_b32_e32 v236, v238
	v_permlane16_swap_b32_e32 v237, v239
	global_store_dwordx4 v[230:231], v[232:235], off
	global_store_dwordx4 v[230:231], v[236:239], off offset:256
	s_and_saveexec_b64 s[18:19], s[42:43]
	s_cbranch_execz .LBB0_526
	s_waitcnt lgkmcnt(0)
	v_add_f32_e32 v18, v18, v19
	ds_write_b32 v0, v18 offset:2560
.LBB0_526:
	s_or_b64 exec, exec, s[18:19]
	v_add_co_u32_e32 v22, vcc, 0xb0000, v180
	s_waitcnt vmcnt(27)
	v_pk_add_f32 v[16:17], v[16:17], v[84:85]
	v_pk_add_f32 v[14:15], v[14:15], v[82:83]
	v_addc_co_u32_e32 v23, vcc, 0, v181, vcc
	global_store_dwordx4 v[22:23], v[14:17], off
	v_mul_f32_e32 v22, v15, v15
	v_fmac_f32_e32 v22, v14, v14
	v_fmac_f32_e32 v22, v16, v16
	v_cvt_pk_bf16_f32 v14, v14, v15
	v_cvt_pk_bf16_f32 v15, v16, v17
	v_add_co_u32_e32 v16, vcc, 0x58000, v178
	s_mov_b64 s[16:17], 0xb0000
	v_fmac_f32_e32 v22, v17, v17
	v_addc_co_u32_e32 v17, vcc, 0, v179, vcc
	s_waitcnt vmcnt(27)
	v_pk_add_f32 v[10:11], v[10:11], v[74:75]
	s_waitcnt lgkmcnt(0)
	v_lshl_add_u64 v[18:19], v[180:181], 0, s[16:17]
	s_mov_b64 s[16:17], 0x58000
	v_mov_b32_e32 v240, v14
	v_mov_b32_e32 v241, v15
	v_pk_add_f32 v[12:13], v[12:13], v[76:77]
	v_mul_f32_e32 v14, v11, v11
	v_lshl_add_u64 v[20:21], v[178:179], 0, s[16:17]
	global_store_dwordx4 v[18:19], v[10:13], off offset:64
	v_fmac_f32_e32 v14, v10, v10
	s_waitcnt vmcnt(28)
	v_pk_add_f32 v[6:7], v[6:7], v[70:71]
	v_cvt_pk_bf16_f32 v10, v10, v11
	v_cvt_pk_bf16_f32 v11, v12, v13
	v_mov_b32_e32 v242, v10
	v_mov_b32_e32 v243, v11
	v_mul_f32_e32 v10, v7, v7
	v_fmac_f32_e32 v14, v12, v12
	v_pk_add_f32 v[8:9], v[8:9], v[72:73]
	v_fmac_f32_e32 v10, v6, v6
	v_fmac_f32_e32 v14, v13, v13
	v_fmac_f32_e32 v10, v8, v8
	v_add_f32_e32 v14, v22, v14
	v_fmac_f32_e32 v10, v9, v9
	v_add_f32_e32 v14, v14, v10
	s_waitcnt vmcnt(28)
	v_pk_add_f32 v[10:11], v[2:3], v[66:67]
	v_pk_add_f32 v[12:13], v[4:5], v[68:69]
	v_mul_f32_e32 v2, v11, v11
	v_fmac_f32_e32 v2, v10, v10
	v_fmac_f32_e32 v2, v12, v12
	v_fmac_f32_e32 v2, v13, v13
	v_add_f32_e32 v4, v14, v2
	ds_bpermute_b32 v5, v184, v4
	v_cvt_pk_bf16_f32 v2, v6, v7
	global_store_dwordx4 v[18:19], v[6:9], off offset:512
	v_cvt_pk_bf16_f32 v3, v8, v9
	v_mov_b32_e32 v244, v2
	v_mov_b32_e32 v245, v3
	s_waitcnt lgkmcnt(0)
	v_add_f32_e32 v2, v4, v5
	ds_bpermute_b32 v3, v146, v2
	global_store_dwordx4 v[18:19], v[10:13], off offset:576
	v_cvt_pk_bf16_f32 v4, v10, v11
	v_cvt_pk_bf16_f32 v5, v12, v13
	v_mov_b32_e32 v246, v4
	v_mov_b32_e32 v247, v5
	v_lshl_add_u64 v[230:231], v[20:21], 0, v[228:229]
	s_waitcnt lgkmcnt(0)
	s_nop 1
	v_permlane16_swap_b32_e32 v240, v242
	v_permlane16_swap_b32_e32 v241, v243
	v_permlane16_swap_b32_e32 v244, v246
	v_permlane16_swap_b32_e32 v245, v247
	global_store_dwordx4 v[230:231], v[240:243], off
	global_store_dwordx4 v[230:231], v[244:247], off offset:256
	s_and_saveexec_b64 s[18:19], s[42:43]
	s_cbranch_execz .LBB0_528
	s_waitcnt lgkmcnt(0)
	v_add_f32_e32 v2, v2, v3
	ds_write_b32 v0, v2 offset:2816
